# same as previous plus s_nop padding so every GEMM/attention K-loop head keeps the baseline's address mod 64 (code-placement control)
# speedup vs baseline: 1.0011x; 1.0011x over previous
;     __device__ __forceinline__ bool next(int i, Unit& u) const { if ((long)i * G + c >= nwg) return false; u.pm = 0; u.pn = 0; return true; }
;     ...
;         const bool has_next = S.next(ui + 1, nxt);
;         const char* nA0 = has_next ? (const char*)g.A + (size_t)nxt.pm * tstep : cA; const char* nB0 = has_next ? (const char*)g.Bt + (size_t)nxt.pn * tstep : cB;
;         int nkb = 0; if constexpr (Sched::SK) { if (has_next) nkb = nxt.kb; }
;         const char* nA = nA0 + (size_t)nkb * kstep; const char* nB = nB0 + (size_t)nkb * kstep;
;     ...
; #pragma unroll
;         for (int a = 0; a < 2; ++a)
; #pragma unroll
;             for (int b = 0; b < 2; ++b)
; #pragma unroll
;                 for (int m = 0; m < 4; ++m)
; #pragma unroll
;                     for (int n = 0; n < 2; ++n) acc[a][b][m][n] = (f32x4){0.f, 0.f, 0.f, 0.f};
;         cur = nxt; cA = nA0; cB = nB0; ++ui; if constexpr (Sched::SK) { kb = cur.kb; ke = cur.ke; }
.LBB0_224:
	s_ashr_i32 s23, s22, 31
	s_lshl_b64 s[68:69], s[22:23], 20
	s_add_u32 s68, s51, s68
	s_addc_u32 s69, s35, s69
	s_and_b64 s[70:71], s[2:3], exec
	s_cselect_b32 s23, s69, s87
	s_cselect_b32 vcc_lo, s68, s86
	s_ashr_i32 s21, s20, 31
	s_lshl_b64 s[70:71], s[20:21], 20
	s_add_u32 s70, s10, s70
	s_addc_u32 s71, s11, s71
	s_and_b64 s[74:75], s[2:3], exec
	s_cselect_b32 s21, s71, s89
	s_cselect_b32 vcc_hi, s70, s88
	s_add_u32 s86, s86, 0x80080
	s_addc_u32 s87, s87, 0
	s_add_u32 s74, s88, 0x100
	v_mov_b32_e32 v34, 0
	s_addc_u32 s75, s89, 0
	s_mov_b32 s76, -2
	v_mov_b32_e32 v35, v34
	v_mov_b32_e32 v36, v34
	v_mov_b32_e32 v37, v34
	v_mov_b32_e32 v38, v34
	v_mov_b32_e32 v39, v34
	v_mov_b32_e32 v40, v34
	v_mov_b32_e32 v41, v34
	v_mov_b32_e32 v50, v34
	v_mov_b32_e32 v51, v34
	v_mov_b32_e32 v52, v34
	v_mov_b32_e32 v53, v34
	v_mov_b32_e32 v54, v34
	v_mov_b32_e32 v55, v34
	v_mov_b32_e32 v56, v34
	v_mov_b32_e32 v57, v34
	v_mov_b32_e32 v66, v34
	v_mov_b32_e32 v67, v34
	v_mov_b32_e32 v68, v34
	v_mov_b32_e32 v69, v34
	v_mov_b32_e32 v70, v34
	v_mov_b32_e32 v71, v34
	v_mov_b32_e32 v72, v34
	v_mov_b32_e32 v73, v34
	v_mov_b32_e32 v82, v34
	v_mov_b32_e32 v83, v34
	v_mov_b32_e32 v84, v34
	v_mov_b32_e32 v85, v34
	v_mov_b32_e32 v86, v34
	v_mov_b32_e32 v87, v34
	v_mov_b32_e32 v88, v34
	v_mov_b32_e32 v89, v34
	v_mov_b32_e32 v42, v34
	v_mov_b32_e32 v43, v34
	v_mov_b32_e32 v44, v34
	v_mov_b32_e32 v45, v34
	v_mov_b32_e32 v46, v34
	v_mov_b32_e32 v47, v34
	v_mov_b32_e32 v48, v34
	v_mov_b32_e32 v49, v34
	v_mov_b32_e32 v58, v34
	v_mov_b32_e32 v59, v34
	v_mov_b32_e32 v60, v34
	v_mov_b32_e32 v61, v34
	v_mov_b32_e32 v62, v34
	v_mov_b32_e32 v63, v34
	v_mov_b32_e32 v64, v34
	v_mov_b32_e32 v65, v34
	v_mov_b32_e32 v74, v34
	v_mov_b32_e32 v75, v34
	v_mov_b32_e32 v76, v34
	v_mov_b32_e32 v77, v34
	v_mov_b32_e32 v78, v34
	v_mov_b32_e32 v79, v34
	v_mov_b32_e32 v80, v34
	v_mov_b32_e32 v81, v34
	v_mov_b32_e32 v90, v34
	v_mov_b32_e32 v91, v34
	v_mov_b32_e32 v92, v34
	v_mov_b32_e32 v93, v34
	v_mov_b32_e32 v94, v34
	v_mov_b32_e32 v95, v34
	v_mov_b32_e32 v96, v34
	v_mov_b32_e32 v97, v34
	v_mov_b32_e32 v98, v34
	v_mov_b32_e32 v99, v34
	v_mov_b32_e32 v100, v34
	v_mov_b32_e32 v101, v34
	v_mov_b32_e32 v102, v34
	v_mov_b32_e32 v103, v34
	v_mov_b32_e32 v104, v34
	v_mov_b32_e32 v105, v34
	v_mov_b32_e32 v114, v34
	v_mov_b32_e32 v115, v34
	v_mov_b32_e32 v116, v34
	v_mov_b32_e32 v117, v34
	v_mov_b32_e32 v118, v34
	v_mov_b32_e32 v119, v34
	v_mov_b32_e32 v120, v34
	v_mov_b32_e32 v121, v34
	v_mov_b32_e32 v130, v34
	v_mov_b32_e32 v131, v34
	v_mov_b32_e32 v132, v34
	v_mov_b32_e32 v133, v34
	v_mov_b32_e32 v134, v34
	v_mov_b32_e32 v135, v34
	v_mov_b32_e32 v136, v34
	v_mov_b32_e32 v137, v34
	v_mov_b32_e32 v146, v34
	v_mov_b32_e32 v147, v34
	v_mov_b32_e32 v148, v34
	v_mov_b32_e32 v149, v34
	v_mov_b32_e32 v150, v34
	v_mov_b32_e32 v151, v34
	v_mov_b32_e32 v152, v34
	v_mov_b32_e32 v153, v34
	v_mov_b32_e32 v106, v34
	v_mov_b32_e32 v107, v34
	v_mov_b32_e32 v108, v34
	v_mov_b32_e32 v109, v34
	v_mov_b32_e32 v110, v34
	v_mov_b32_e32 v111, v34
	v_mov_b32_e32 v112, v34
	v_mov_b32_e32 v113, v34
	v_mov_b32_e32 v122, v34
	v_mov_b32_e32 v123, v34
	v_mov_b32_e32 v124, v34
	v_mov_b32_e32 v125, v34
	v_mov_b32_e32 v126, v34
	v_mov_b32_e32 v127, v34
	v_mov_b32_e32 v128, v34
	v_mov_b32_e32 v129, v34
	v_mov_b32_e32 v138, v34
	v_mov_b32_e32 v139, v34
	v_mov_b32_e32 v140, v34
	v_mov_b32_e32 v141, v34
	v_mov_b32_e32 v142, v34
	v_mov_b32_e32 v143, v34
	v_mov_b32_e32 v144, v34
	v_mov_b32_e32 v145, v34
	v_mov_b32_e32 v154, v34
	v_mov_b32_e32 v155, v34
	v_mov_b32_e32 v156, v34
	v_mov_b32_e32 v157, v34
	v_mov_b32_e32 v158, v34
	v_mov_b32_e32 v159, v34
	v_mov_b32_e32 v160, v34
	v_mov_b32_e32 v161, v34
	s_nop 0
	s_nop 0
	s_nop 0
	s_nop 0
	s_nop 0
	s_nop 0
	s_nop 0
	s_nop 0
	s_nop 0
	s_nop 0
	s_nop 0
	s_nop 0
	s_nop 0
	s_nop 0
	s_nop 0

;     __device__ __forceinline__ bool next(int i, Unit& u) const { if ((long)i * G + c >= nwg) return false; u.pm = 0; u.pn = 0; return true; }
;     ...
;         const bool has_next = S.next(ui + 1, nxt);
;         const char* nA0 = has_next ? (const char*)g.A + (size_t)nxt.pm * tstep : cA; const char* nB0 = has_next ? (const char*)g.Bt + (size_t)nxt.pn * tstep : cB;
;         int nkb = 0; if constexpr (Sched::SK) { if (has_next) nkb = nxt.kb; }
;         const char* nA = nA0 + (size_t)nkb * kstep; const char* nB = nB0 + (size_t)nkb * kstep;
;     ...
; #pragma unroll
;         for (int a = 0; a < 2; ++a)
; #pragma unroll
;             for (int b = 0; b < 2; ++b)
; #pragma unroll
;                 for (int m = 0; m < 4; ++m)
; #pragma unroll
;                     for (int n = 0; n < 2; ++n) acc[a][b][m][n] = (f32x4){0.f, 0.f, 0.f, 0.f};
;         cur = nxt; cA = nA0; cB = nB0; ++ui; if constexpr (Sched::SK) { kb = cur.kb; ke = cur.ke; }
.LBB0_504:
	s_ashr_i32 s19, s18, 31
	s_lshl_b64 s[20:21], s[18:19], 20
	s_add_u32 s20, s27, s20
	s_addc_u32 s21, s34, s21
	s_and_b64 s[22:23], s[2:3], exec
	s_cselect_b32 s19, s21, s75
	s_cselect_b32 s95, s20, s74
	s_ashr_i32 s17, s16, 31
	s_lshl_b64 s[22:23], s[16:17], 20
	s_add_u32 s22, s84, s22
	s_addc_u32 s23, s85, s23
	s_and_b64 s[78:79], s[2:3], exec
	s_cselect_b32 s17, s23, s77
	s_cselect_b32 s96, s22, s76
	s_add_u32 s74, s74, 0x80080
	s_addc_u32 s75, s75, 0
	s_add_u32 s80, s76, 0x100
	v_mov_b32_e32 v34, 0
	s_addc_u32 s81, s77, 0
	s_mov_b32 s82, -2
	v_mov_b32_e32 v35, v34
	v_mov_b32_e32 v36, v34
	v_mov_b32_e32 v37, v34
	v_mov_b32_e32 v38, v34
	v_mov_b32_e32 v39, v34
	v_mov_b32_e32 v40, v34
	v_mov_b32_e32 v41, v34
	v_mov_b32_e32 v46, v34
	v_mov_b32_e32 v47, v34
	v_mov_b32_e32 v48, v34
	v_mov_b32_e32 v49, v34
	v_mov_b32_e32 v54, v34
	v_mov_b32_e32 v55, v34
	v_mov_b32_e32 v56, v34
	v_mov_b32_e32 v57, v34
	v_mov_b32_e32 v62, v34
	v_mov_b32_e32 v63, v34
	v_mov_b32_e32 v64, v34
	v_mov_b32_e32 v65, v34
	v_mov_b32_e32 v70, v34
	v_mov_b32_e32 v71, v34
	v_mov_b32_e32 v72, v34
	v_mov_b32_e32 v73, v34
	v_mov_b32_e32 v78, v34
	v_mov_b32_e32 v79, v34
	v_mov_b32_e32 v80, v34
	v_mov_b32_e32 v81, v34
	v_mov_b32_e32 v86, v34
	v_mov_b32_e32 v87, v34
	v_mov_b32_e32 v88, v34
	v_mov_b32_e32 v89, v34
	v_mov_b32_e32 v42, v34
	v_mov_b32_e32 v43, v34
	v_mov_b32_e32 v44, v34
	v_mov_b32_e32 v45, v34
	v_mov_b32_e32 v50, v34
	v_mov_b32_e32 v51, v34
	v_mov_b32_e32 v52, v34
	v_mov_b32_e32 v53, v34
	v_mov_b32_e32 v58, v34
	v_mov_b32_e32 v59, v34
	v_mov_b32_e32 v60, v34
	v_mov_b32_e32 v61, v34
	v_mov_b32_e32 v66, v34
	v_mov_b32_e32 v67, v34
	v_mov_b32_e32 v68, v34
	v_mov_b32_e32 v69, v34
	v_mov_b32_e32 v74, v34
	v_mov_b32_e32 v75, v34
	v_mov_b32_e32 v76, v34
	v_mov_b32_e32 v77, v34
	v_mov_b32_e32 v82, v34
	v_mov_b32_e32 v83, v34
	v_mov_b32_e32 v84, v34
	v_mov_b32_e32 v85, v34
	v_mov_b32_e32 v90, v34
	v_mov_b32_e32 v91, v34
	v_mov_b32_e32 v92, v34
	v_mov_b32_e32 v93, v34
	v_mov_b32_e32 v94, v34
	v_mov_b32_e32 v95, v34
	v_mov_b32_e32 v96, v34
	v_mov_b32_e32 v97, v34
	v_mov_b32_e32 v98, v34
	v_mov_b32_e32 v99, v34
	v_mov_b32_e32 v100, v34
	v_mov_b32_e32 v101, v34
	v_mov_b32_e32 v102, v34
	v_mov_b32_e32 v103, v34
	v_mov_b32_e32 v104, v34
	v_mov_b32_e32 v105, v34
	v_mov_b32_e32 v110, v34
	v_mov_b32_e32 v111, v34
	v_mov_b32_e32 v112, v34
	v_mov_b32_e32 v113, v34
	v_mov_b32_e32 v118, v34
	v_mov_b32_e32 v119, v34
	v_mov_b32_e32 v120, v34
	v_mov_b32_e32 v121, v34
	v_mov_b32_e32 v126, v34
	v_mov_b32_e32 v127, v34
	v_mov_b32_e32 v128, v34
	v_mov_b32_e32 v129, v34
	v_mov_b32_e32 v134, v34
	v_mov_b32_e32 v135, v34
	v_mov_b32_e32 v136, v34
	v_mov_b32_e32 v137, v34
	v_mov_b32_e32 v142, v34
	v_mov_b32_e32 v143, v34
	v_mov_b32_e32 v144, v34
	v_mov_b32_e32 v145, v34
	v_mov_b32_e32 v150, v34
	v_mov_b32_e32 v151, v34
	v_mov_b32_e32 v152, v34
	v_mov_b32_e32 v153, v34
	v_mov_b32_e32 v106, v34
	v_mov_b32_e32 v107, v34
	v_mov_b32_e32 v108, v34
	v_mov_b32_e32 v109, v34
	v_mov_b32_e32 v114, v34
	v_mov_b32_e32 v115, v34
	v_mov_b32_e32 v116, v34
	v_mov_b32_e32 v117, v34
	v_mov_b32_e32 v122, v34
	v_mov_b32_e32 v123, v34
	v_mov_b32_e32 v124, v34
	v_mov_b32_e32 v125, v34
	v_mov_b32_e32 v130, v34
	v_mov_b32_e32 v131, v34
	v_mov_b32_e32 v132, v34
	v_mov_b32_e32 v133, v34
	v_mov_b32_e32 v138, v34
	v_mov_b32_e32 v139, v34
	v_mov_b32_e32 v140, v34
	v_mov_b32_e32 v141, v34
	v_mov_b32_e32 v146, v34
	v_mov_b32_e32 v147, v34
	v_mov_b32_e32 v148, v34
	v_mov_b32_e32 v149, v34
	v_mov_b32_e32 v154, v34
	v_mov_b32_e32 v155, v34
	v_mov_b32_e32 v156, v34
	v_mov_b32_e32 v157, v34
	v_mov_b32_e32 v158, v34
	v_mov_b32_e32 v159, v34
	v_mov_b32_e32 v160, v34
	v_mov_b32_e32 v161, v34
	s_nop 0
	s_nop 0
	s_nop 0

; #define GAS __attribute__((address_space(1)))
; __device__ __forceinline__ void prompt_unit(Frame& F, const Args& A, int b, int hk) {
;     ...
;     const int g = F.wave >> 1, half = F.wave & 1, c = F.lane & 31, h = F.lane >> 5, head = 4 * hk + g;
;     const float sink = A.in[I_SINK][head];
; #pragma unroll 1
;     for (int qt = 0; qt < 2; ++qt) { const int r = 64 * half + 32 * qt + c, row = 128 * b + r;
;         bf16x8 Q[8];
; #pragma unroll
;         for (int ks = 0; ks < 8; ++ks) Q[ks] = *(const GAS bf16x8*)(PROJ + (size_t)row * NPROJ + 128 * head + 16 * ks + 8 * h);
;         attn_qtile<5>(lds, 2 * half + qt, Q, r, b == 0 ? 128 : 0, 256, g, sink, MIX + (size_t)row * D + 128 * head, F.lane);
.LBB0_624:
	s_lshl_b32 s0, s0, 2
	s_add_i32 s0, s0, s15
	s_lshl_b32 s1, s0, 2
	v_readlane_b32 s76, v252, 3
	v_mov_b32_e32 v2, s1
	v_readlane_b32 s88, v252, 15
	v_readlane_b32 s89, v252, 16
	s_waitcnt lgkmcnt(0)
	s_barrier
	s_lshl_b32 s8, s0, 8
	s_and_b64 s[6:7], s[10:11], exec
	s_nop 0
	global_load_dword v185, v2, s[88:89]
	v_lshl_add_u64 v[144:145], v[114:115], 0, s[8:9]
	s_mov_b32 s0, 0
	s_cselect_b32 s12, 0x80, 0
	v_lshl_add_u64 v[146:147], v[116:117], 0, s[8:9]
	s_mov_b64 s[10:11], -1
	v_readlane_b32 s77, v252, 4
	v_readlane_b32 s78, v252, 5
	v_readlane_b32 s79, v252, 6
	v_readlane_b32 s80, v252, 7
	v_readlane_b32 s81, v252, 8
	v_readlane_b32 s82, v252, 9
	v_readlane_b32 s83, v252, 10
	v_readlane_b32 s84, v252, 11
	v_readlane_b32 s85, v252, 12
	v_readlane_b32 s86, v252, 13
	v_readlane_b32 s87, v252, 14
	v_readlane_b32 s90, v252, 17
	v_readlane_b32 s91, v252, 18
	s_nop 0
	s_nop 0
	s_nop 0
	s_nop 0
	s_nop 0
	s_nop 0
	s_nop 0
	s_nop 0
	s_nop 0
	s_nop 0
	s_nop 0
	s_nop 0
	s_nop 0
	s_nop 0
	s_nop 0
